# P0 rmsnorm pass: wave sum by DPP adds and permlane swaps instead of six ds_bpermute round trips per row
# speedup vs baseline: 1.0051x; 1.0014x over previous
; __device__ __forceinline__ void rms_pass(const float* X, const float* g, bf16_t* O, float* F, int rows, int gw, int NGW) {
;     ...
;     for (int m = gw; m < rows; m += 2 * NGW) {
;         const bool two = (m + NGW) < rows; const int m1 = two ? m + NGW : m;
;         const f32x4* x0 = (const f32x4*)(X + (size_t)m * 1024) + lane; const f32x4* x1 = (const f32x4*)(X + (size_t)m1 * 1024) + lane;
;         f32x4 v0[4], v1[4]; float s0 = 0.f, s1 = 0.f;
; #pragma unroll
;         for (int j = 0; j < 4; ++j) { v0[j] = x0[64 * j]; v1[j] = x1[64 * j]; }
; #pragma unroll
;         for (int j = 0; j < 4; ++j) { s0 += (v0[j].x * v0[j].x + v0[j].y * v0[j].y) + (v0[j].z * v0[j].z + v0[j].w * v0[j].w); s1 += (v1[j].x * v1[j].x + v1[j].y * v1[j].y) + (v1[j].z * v1[j].z + v1[j].w * v1[j].w); }
.LBB0_1323:
	s_add_i32 s26, s6, s77
	s_cmp_lt_i32 s26, 0x10000
	s_cselect_b64 s[14:15], -1, 0
	s_and_b64 s[8:9], s[14:15], exec
	s_cselect_b32 s8, s26, s6
	s_ashr_i32 s7, s6, 31
	s_lshl_b64 s[30:31], s[6:7], 12
	s_ashr_i32 s9, s8, 31
	s_waitcnt vmcnt(4)
	v_mov_b64_e32 v[26:27], v[224:225]
	v_mov_b64_e32 v[28:29], v[226:227]
	v_mov_b64_e32 v[18:19], v[228:229]
	v_mov_b64_e32 v[20:21], v[230:231]
	v_mov_b64_e32 v[2:3], v[232:233]
	v_mov_b64_e32 v[4:5], v[234:235]
	v_mov_b64_e32 v[14:15], v[236:237]
	v_mov_b64_e32 v[16:17], v[238:239]
	v_mov_b64_e32 v[30:31], v[240:241]
	v_mov_b64_e32 v[32:33], v[242:243]
	v_mov_b64_e32 v[22:23], v[244:245]
	v_mov_b64_e32 v[24:25], v[246:247]
	v_mov_b64_e32 v[6:7], v[248:249]
	v_mov_b64_e32 v[8:9], v[250:251]
	v_mov_b64_e32 v[10:11], v[200:201]
	v_mov_b64_e32 v[12:13], v[202:203]
	s_add_i32 s98, s26, s77
	s_cmp_lt_i32 s98, 0x10000
	s_cselect_b32 s98, s98, s6
	s_mov_b32 s99, 0
	s_add_i32 s100, s98, s77
	s_cmp_lt_i32 s100, 0x10000
	s_cselect_b32 s100, s100, s98
	s_mov_b32 s101, 0
	s_lshl_b64 s[98:99], s[98:99], 12
	v_lshl_add_u64 v[204:205], v[36:37], 0, s[98:99]
	global_load_dwordx4 v[224:227], v[204:205], off
	global_load_dwordx4 v[228:231], v[204:205], off offset:1024
	global_load_dwordx4 v[232:235], v[204:205], off offset:3072
	global_load_dwordx4 v[236:239], v[204:205], off offset:2048
	s_lshl_b64 s[100:101], s[100:101], 12
	v_lshl_add_u64 v[206:207], v[36:37], 0, s[100:101]
	global_load_dwordx4 v[240:243], v[206:207], off
	global_load_dwordx4 v[244:247], v[206:207], off offset:1024
	global_load_dwordx4 v[248:251], v[206:207], off offset:3072
	global_load_dwordx4 v[200:203], v[206:207], off offset:2048
	s_lshl_b64 s[30:31], s[6:7], 11
	s_lshl_b64 s[34:35], s[8:9], 11
	s_cmp_gt_i32 s26, 0xffff
	v_pk_mul_f32 v[42:43], v[28:29], v[28:29]
	v_pk_mul_f32 v[44:45], v[26:27], v[26:27]
	v_pk_mul_f32 v[46:47], v[20:21], v[20:21]
	v_pk_mul_f32 v[48:49], v[18:19], v[18:19]
	v_mul_f32_e32 v58, v15, v15
	v_mul_f32_e32 v60, v17, v17
	v_pk_mov_b32 v[62:63], v[44:45], v[42:43] op_sel:[1,0]
	v_mov_b32_e32 v45, v43
	v_pk_mul_f32 v[42:43], v[32:33], v[32:33]
	v_pk_mul_f32 v[64:65], v[30:31], v[30:31]
	v_pk_mov_b32 v[66:67], v[48:49], v[46:47] op_sel:[1,0]
	v_mov_b32_e32 v49, v47
	v_pk_mul_f32 v[46:47], v[24:25], v[24:25]
	v_pk_mul_f32 v[68:69], v[22:23], v[22:23]
	v_mul_f32_e32 v57, v4, v4
	v_mul_f32_e32 v71, v5, v5
	v_pk_fma_f32 v[58:59], v[14:15], v[14:15], v[58:59] op_sel_hi:[1,1,0]
	v_pk_fma_f32 v[60:61], v[16:17], v[16:17], v[60:61] op_sel_hi:[1,1,0]
	v_pk_add_f32 v[44:45], v[62:63], v[44:45]
	v_pk_mov_b32 v[62:63], v[64:65], v[42:43] op_sel:[1,0]
	v_mov_b32_e32 v65, v43
	v_pk_add_f32 v[42:43], v[66:67], v[48:49]
	v_pk_mov_b32 v[48:49], v[68:69], v[46:47] op_sel:[1,0]
	v_mov_b32_e32 v69, v47
	v_mul_f32_e32 v73, v2, v2
	v_mul_f32_e32 v74, v3, v3
	v_mov_b32_e32 v59, v57
	v_mov_b32_e32 v61, v71
	v_pk_add_f32 v[62:63], v[62:63], v[64:65]
	v_pk_add_f32 v[48:49], v[48:49], v[68:69]
	v_pk_add_f32 v[44:45], v[44:45], v[44:45] op_sel:[0,1] op_sel_hi:[1,0]
	v_pk_add_f32 v[42:43], v[42:43], v[42:43] op_sel:[0,1] op_sel_hi:[1,0]
	v_mul_f32_e32 v77, v6, v6
	v_mul_f32_e32 v78, v7, v7
	v_pk_add_f32 v[58:59], v[58:59], v[60:61]
	v_mov_b32_e32 v45, v73
	v_mov_b32_e32 v43, v74
	v_pk_add_f32 v[60:61], v[62:63], v[62:63] op_sel:[0,1] op_sel_hi:[1,0]
	v_pk_add_f32 v[48:49], v[48:49], v[48:49] op_sel:[0,1] op_sel_hi:[1,0]
	v_pk_add_f32 v[42:43], v[44:45], v[42:43]
	v_mov_b32_e32 v61, v77
	v_mov_b32_e32 v49, v78
	v_pk_add_f32 v[42:43], v[42:43], v[58:59]
	v_pk_add_f32 v[44:45], v[60:61], v[48:49]
	v_mul_f32_e32 v70, v11, v11
	v_mul_f32_e32 v72, v13, v13
	v_mul_f32_e32 v75, v8, v8
	v_mul_f32_e32 v76, v9, v9
	v_pk_fma_f32 v[46:47], v[10:11], v[10:11], v[70:71] op_sel_hi:[1,1,0]
	v_pk_fma_f32 v[66:67], v[12:13], v[12:13], v[72:73] op_sel_hi:[1,1,0]
	v_mov_b32_e32 v47, v75
	v_mov_b32_e32 v67, v76
	v_pk_add_f32 v[46:47], v[46:47], v[66:67]
; __device__ __forceinline__ float wave_sum(float v) {
; #pragma unroll
;     for (int o = 1; o < 64; o <<= 1) v += __shfl_xor(v, o);
;     return v;
; }
; __device__ __forceinline__ void rms_pass(const float* X, const float* g, bf16_t* O, float* F, int rows, int gw, int NGW) {
;     ...
;         const float r0 = 1.0f / sqrtf(wave_sum(s0) * (1.f / 1024.f) + 1e-6f), r1 = 1.0f / sqrtf(wave_sum(s1) * (1.f / 1024.f) + 1e-6f);
	v_add_f32_e32 v48, v42, v43
	v_pk_add_f32 v[42:43], v[44:45], v[46:47]
	v_add_f32_e32 v42, v42, v43
	v_mov_b32_e32 v44, v48
	s_nop 1
	v_add_f32_dpp v44, v44, v44 quad_perm:[1,0,3,2] row_mask:0xf bank_mask:0xf
	v_add_f32_dpp v42, v42, v42 quad_perm:[1,0,3,2] row_mask:0xf bank_mask:0xf
	s_nop 0
	v_add_f32_dpp v44, v44, v44 quad_perm:[2,3,0,1] row_mask:0xf bank_mask:0xf
	v_add_f32_dpp v42, v42, v42 quad_perm:[2,3,0,1] row_mask:0xf bank_mask:0xf
	s_nop 0
	v_add_f32_dpp v44, v44, v44 row_half_mirror row_mask:0xf bank_mask:0xf
	v_add_f32_dpp v42, v42, v42 row_half_mirror row_mask:0xf bank_mask:0xf
	s_nop 0
	v_add_f32_dpp v44, v44, v44 row_mirror row_mask:0xf bank_mask:0xf
	v_add_f32_dpp v42, v42, v42 row_mirror row_mask:0xf bank_mask:0xf
	s_nop 0
	v_mov_b32_e32 v45, v44
	v_mov_b32_e32 v43, v42
	s_nop 1
	v_permlane16_swap_b32_e32 v44, v45
	v_permlane16_swap_b32_e32 v42, v43
	s_nop 1
	v_add_f32_e32 v44, v44, v45
	v_add_f32_e32 v42, v42, v43
	v_mov_b32_e32 v45, v44
	v_mov_b32_e32 v43, v42
	s_nop 1
	v_permlane32_swap_b32_e32 v44, v45
	v_permlane32_swap_b32_e32 v42, v43
	s_nop 1
	v_add_f32_e32 v44, v44, v45
	v_add_f32_e32 v42, v42, v43
	v_fmamk_f32 v44, v44, 0x3a800000, v55
	v_mul_f32_e32 v43, 0x4f800000, v44
	v_cmp_gt_f32_e32 vcc, s13, v44
	v_fmamk_f32 v42, v42, 0x3a800000, v55
	v_cmp_gt_f32_e64 s[6:7], s13, v42
	v_cndmask_b32_e32 v43, v44, v43, vcc
	v_mul_f32_e32 v44, 0x4f800000, v42
	v_sqrt_f32_e32 v45, v43
	v_cndmask_b32_e64 v42, v42, v44, s[6:7]
	v_sqrt_f32_e32 v44, v42
	v_add_u32_e32 v46, -1, v45
	v_add_u32_e32 v47, 1, v45
	v_fma_f32 v48, -v46, v45, v43
	v_fma_f32 v49, -v47, v45, v43
	v_add_u32_e32 v57, -1, v44
	v_cmp_ge_f32_e64 s[8:9], 0, v48
	v_add_u32_e32 v62, 1, v44
	v_fma_f32 v48, -v62, v44, v42
	v_cndmask_b32_e64 v45, v45, v46, s[8:9]
	v_fma_f32 v46, -v57, v44, v42
	v_cmp_lt_f32_e64 s[8:9], 0, v49
	s_nop 1
	v_cndmask_b32_e64 v45, v45, v47, s[8:9]
	v_cmp_ge_f32_e64 s[8:9], 0, v46
	v_mul_f32_e32 v46, 0x37800000, v45
	v_cndmask_b32_e32 v45, v45, v46, vcc
	v_cndmask_b32_e64 v44, v44, v57, s[8:9]
	v_cmp_lt_f32_e64 s[8:9], 0, v48
	v_cmp_class_f32_e32 vcc, v43, v56
	s_nop 0
	v_cndmask_b32_e64 v44, v44, v62, s[8:9]
	v_mul_f32_e32 v46, 0x37800000, v44
	v_cndmask_b32_e32 v43, v45, v43, vcc
	v_cndmask_b32_e64 v44, v44, v46, s[6:7]
	v_div_scale_f32 v45, s[6:7], v43, v43, 1.0
	v_cmp_class_f32_e64 s[6:7], v42, v56
	v_div_scale_f32 v46, vcc, 1.0, v43, 1.0
	s_nop 0
	v_cndmask_b32_e64 v42, v44, v42, s[6:7]
	v_rcp_f32_e32 v44, v45
	v_div_scale_f32 v47, s[6:7], v42, v42, 1.0
	v_rcp_f32_e32 v49, v47
	v_fma_f32 v48, -v45, v44, 1.0
	v_fmac_f32_e32 v44, v48, v44
	v_mul_f32_e32 v62, v46, v44
	v_fma_f32 v48, -v47, v49, 1.0
	v_fmac_f32_e32 v49, v48, v49
	v_fma_f32 v48, -v45, v62, v46
	v_fmac_f32_e32 v62, v48, v44
	v_fma_f32 v45, -v45, v62, v46
	v_div_scale_f32 v57, s[6:7], 1.0, v42, 1.0
	v_div_fmas_f32 v44, v45, v44, v62
	v_div_fixup_f32 v48, v44, v43, 1.0
	v_mul_f32_e32 v43, v57, v49
	v_fma_f32 v44, -v47, v43, v57
	v_fmac_f32_e32 v43, v44, v49
	v_fma_f32 v44, -v47, v43, v57
	s_mov_b64 vcc, s[6:7]
	v_div_fmas_f32 v43, v44, v49, v43
	v_div_fixup_f32 v46, v43, v42, 1.0
	v_pk_mul_f32 v[26:27], v[26:27], v[48:49] op_sel_hi:[1,0]
	v_lshl_add_u64 v[44:45], v[40:41], 0, s[30:31]
	v_lshl_add_u64 v[42:43], v[40:41], 0, s[34:35]
	v_pk_mul_f32 v[28:29], v[28:29], v[48:49] op_sel_hi:[1,0]
	v_pk_mul_f32 v[26:27], v[208:209], v[26:27]
	v_pk_mul_f32 v[30:31], v[30:31], v[46:47] op_sel_hi:[1,0]
	v_pk_mul_f32 v[32:33], v[32:33], v[46:47] op_sel_hi:[1,0]
	v_pk_mul_f32 v[28:29], v[210:211], v[28:29]
	v_pk_mul_f32 v[32:33], v[210:211], v[32:33]
	v_pk_mul_f32 v[30:31], v[208:209], v[30:31]
	v_cvt_pk_bf16_f32 v58, v26, v27
	v_cvt_pk_bf16_f32 v59, v28, v29
	s_nop 0
	v_cvt_pk_bf16_f32 v26, v30, v31
	v_cvt_pk_bf16_f32 v27, v32, v33
	global_store_dwordx2 v[44:45], v[58:59], off
	s_cbranch_scc1 .LBB0_1325
	global_store_dwordx2 v[42:43], v[26:27], off
